# serpentine MFMA order inside each 16-MFMA block of the up/down K-loops (one operand switches per step instead of 1.5; k0-before-k1 per accumulator kept, bit-identical) on top of P0 de-serialisation +
# baseline (speedup 1.0000x reference)
.LBB0_535:
	ds_read_b128 v[150:153], v128
	ds_read_b128 v[154:157], v128 offset:1024
	ds_read_b128 v[158:161], v128 offset:2048
	ds_read_b128 v[170:173], v128 offset:3072
	ds_read_b128 v[174:177], v146
	ds_read_b128 v[178:181], v146 offset:1024
	ds_read_b128 v[182:185], v146 offset:2048
	ds_read_b128 v[186:189], v146 offset:3072
	s_cmp_eq_u32 s16, 60
	s_cselect_b32 s62, s94, vcc_lo
	s_cselect_b32 s63, s53, vcc_hi
	s_cselect_b32 s60, s95, s14
	s_cselect_b32 s61, s41, s15
	s_add_u32 s58, s62, 0x8000
	s_addc_u32 s59, s63, 0
	ds_read_b128 v[190:193], v147
	ds_read_b128 v[194:197], v147 offset:1024
	ds_read_b128 v[198:201], v147 offset:2048
	ds_read_b128 v[202:205], v147 offset:3072
	ds_read_b128 v[206:209], v147 offset:4096
	ds_read_b128 v[210:213], v147 offset:5120
	ds_read_b128 v[214:217], v147 offset:6144
	ds_read_b128 v[218:221], v147 offset:7168
	s_add_u32 s18, vcc_lo, 0xffffc000
	s_addc_u32 s19, vcc_hi, -1
	s_mov_b32 m0, s89
	s_nop 0
	global_load_lds_dwordx4 v142, s[18:19]
	s_nop 0
	s_mov_b32 m0, s90
	s_nop 0
	global_load_lds_dwordx4 v144, s[18:19]
	s_waitcnt vmcnt(8)
	s_waitcnt lgkmcnt(0)
	s_setprio 1
	s_barrier
	v_mfma_f32_16x16x32_bf16 v[124:127], v[150:153], v[190:193], v[124:127]
	v_mfma_f32_16x16x32_bf16 v[120:123], v[158:161], v[190:193], v[120:123]
	v_mfma_f32_16x16x32_bf16 v[104:107], v[158:161], v[198:201], v[104:107]
	v_mfma_f32_16x16x32_bf16 v[108:111], v[150:153], v[198:201], v[108:111]
	v_mfma_f32_16x16x32_bf16 v[92:95], v[150:153], v[206:209], v[92:95]
	v_mfma_f32_16x16x32_bf16 v[88:91], v[158:161], v[206:209], v[88:91]
	v_mfma_f32_16x16x32_bf16 v[72:75], v[158:161], v[214:217], v[72:75]
	v_mfma_f32_16x16x32_bf16 v[76:79], v[150:153], v[214:217], v[76:79]
	v_mfma_f32_16x16x32_bf16 v[76:79], v[154:157], v[218:221], v[76:79]
	v_mfma_f32_16x16x32_bf16 v[72:75], v[170:173], v[218:221], v[72:75]
	v_mfma_f32_16x16x32_bf16 v[88:91], v[170:173], v[210:213], v[88:91]
	v_mfma_f32_16x16x32_bf16 v[92:95], v[154:157], v[210:213], v[92:95]
	v_mfma_f32_16x16x32_bf16 v[108:111], v[154:157], v[202:205], v[108:111]
	v_mfma_f32_16x16x32_bf16 v[104:107], v[170:173], v[202:205], v[104:107]
	v_mfma_f32_16x16x32_bf16 v[120:123], v[170:173], v[194:197], v[120:123]
	v_mfma_f32_16x16x32_bf16 v[124:127], v[154:157], v[194:197], v[124:127]
	s_setprio 0
	s_setprio 1
	v_mfma_f32_16x16x32_bf16 v[116:119], v[174:177], v[190:193], v[116:119]
	v_mfma_f32_16x16x32_bf16 v[112:115], v[182:185], v[190:193], v[112:115]
	v_mfma_f32_16x16x32_bf16 v[96:99], v[182:185], v[198:201], v[96:99]
	v_mfma_f32_16x16x32_bf16 v[100:103], v[174:177], v[198:201], v[100:103]
	v_mfma_f32_16x16x32_bf16 v[84:87], v[174:177], v[206:209], v[84:87]
	v_mfma_f32_16x16x32_bf16 v[80:83], v[182:185], v[206:209], v[80:83]
	v_mfma_f32_16x16x32_bf16 v[64:67], v[182:185], v[214:217], v[64:67]
	v_mfma_f32_16x16x32_bf16 v[68:71], v[174:177], v[214:217], v[68:71]
	v_mfma_f32_16x16x32_bf16 v[68:71], v[178:181], v[218:221], v[68:71]
	v_mfma_f32_16x16x32_bf16 v[64:67], v[186:189], v[218:221], v[64:67]
	v_mfma_f32_16x16x32_bf16 v[80:83], v[186:189], v[210:213], v[80:83]
	v_mfma_f32_16x16x32_bf16 v[84:87], v[178:181], v[210:213], v[84:87]
	v_mfma_f32_16x16x32_bf16 v[100:103], v[178:181], v[202:205], v[100:103]
	v_mfma_f32_16x16x32_bf16 v[96:99], v[186:189], v[202:205], v[96:99]
	v_mfma_f32_16x16x32_bf16 v[112:115], v[186:189], v[194:197], v[112:115]
	v_mfma_f32_16x16x32_bf16 v[116:119], v[178:181], v[194:197], v[116:119]
	s_setprio 0
	s_barrier
	ds_read_b128 v[190:193], v147 offset:16384
	ds_read_b128 v[194:197], v147 offset:17408
	ds_read_b128 v[198:201], v147 offset:18432
	ds_read_b128 v[202:205], v147 offset:19456
	ds_read_b128 v[206:209], v147 offset:20480
	ds_read_b128 v[210:213], v147 offset:21504
	ds_read_b128 v[214:217], v147 offset:22528
	ds_read_b128 v[218:221], v147 offset:23552
	s_mov_b32 m0, s45
	s_nop 0
	global_load_lds_dwordx4 v143, s[60:61]
	s_add_u32 s18, s60, 0x4000
	s_mov_b32 m0, s46
	s_nop 0
	global_load_lds_dwordx4 v145, s[60:61]
	s_addc_u32 s19, s61, 0
	s_mov_b32 m0, s47
	s_nop 0
	global_load_lds_dwordx4 v143, s[18:19]
	s_nop 0
	s_mov_b32 m0, s64
	s_nop 0
	global_load_lds_dwordx4 v145, s[18:19]
	s_nop 0
	s_mov_b32 m0, s44
	s_nop 0
	global_load_lds_dwordx4 v142, s[62:63]
	s_nop 0
	s_mov_b32 m0, s65
	s_nop 0
	global_load_lds_dwordx4 v144, s[62:63]
	s_waitcnt vmcnt(8)
	s_waitcnt lgkmcnt(0)
	s_setprio 1
	s_barrier
	v_mfma_f32_16x16x32_bf16 v[60:63], v[150:153], v[190:193], v[60:63]
	v_mfma_f32_16x16x32_bf16 v[56:59], v[158:161], v[190:193], v[56:59]
	v_mfma_f32_16x16x32_bf16 v[40:43], v[158:161], v[198:201], v[40:43]
	v_mfma_f32_16x16x32_bf16 v[44:47], v[150:153], v[198:201], v[44:47]
	v_mfma_f32_16x16x32_bf16 v[28:31], v[150:153], v[206:209], v[28:31]
	v_mfma_f32_16x16x32_bf16 v[24:27], v[158:161], v[206:209], v[24:27]
	v_mfma_f32_16x16x32_bf16 v[8:11], v[158:161], v[214:217], v[8:11]
	v_mfma_f32_16x16x32_bf16 v[12:15], v[150:153], v[214:217], v[12:15]
	v_mfma_f32_16x16x32_bf16 v[12:15], v[154:157], v[218:221], v[12:15]
	v_mfma_f32_16x16x32_bf16 v[8:11], v[170:173], v[218:221], v[8:11]
	v_mfma_f32_16x16x32_bf16 v[24:27], v[170:173], v[210:213], v[24:27]
	v_mfma_f32_16x16x32_bf16 v[28:31], v[154:157], v[210:213], v[28:31]
	v_mfma_f32_16x16x32_bf16 v[44:47], v[154:157], v[202:205], v[44:47]
	v_mfma_f32_16x16x32_bf16 v[40:43], v[170:173], v[202:205], v[40:43]
	v_mfma_f32_16x16x32_bf16 v[56:59], v[170:173], v[194:197], v[56:59]
	v_mfma_f32_16x16x32_bf16 v[60:63], v[154:157], v[194:197], v[60:63]
	s_setprio 0
	s_setprio 1
	v_mfma_f32_16x16x32_bf16 v[52:55], v[174:177], v[190:193], v[52:55]
	v_mfma_f32_16x16x32_bf16 v[48:51], v[182:185], v[190:193], v[48:51]
	v_mfma_f32_16x16x32_bf16 v[32:35], v[182:185], v[198:201], v[32:35]
	v_mfma_f32_16x16x32_bf16 v[36:39], v[174:177], v[198:201], v[36:39]
	v_mfma_f32_16x16x32_bf16 v[20:23], v[174:177], v[206:209], v[20:23]
	v_mfma_f32_16x16x32_bf16 v[16:19], v[182:185], v[206:209], v[16:19]
	v_mfma_f32_16x16x32_bf16 v[0:3], v[182:185], v[214:217], v[0:3]
	v_mfma_f32_16x16x32_bf16 v[4:7], v[174:177], v[214:217], v[4:7]
	v_mfma_f32_16x16x32_bf16 v[4:7], v[178:181], v[218:221], v[4:7]
	v_mfma_f32_16x16x32_bf16 v[0:3], v[186:189], v[218:221], v[0:3]
	v_mfma_f32_16x16x32_bf16 v[16:19], v[186:189], v[210:213], v[16:19]
	v_mfma_f32_16x16x32_bf16 v[20:23], v[178:181], v[210:213], v[20:23]
	v_mfma_f32_16x16x32_bf16 v[36:39], v[178:181], v[202:205], v[36:39]
	v_mfma_f32_16x16x32_bf16 v[32:35], v[186:189], v[202:205], v[32:35]
	v_mfma_f32_16x16x32_bf16 v[48:51], v[186:189], v[194:197], v[48:51]
	v_mfma_f32_16x16x32_bf16 v[52:55], v[178:181], v[194:197], v[52:55]
	s_setprio 0
	s_barrier
	ds_read_b128 v[150:153], v148
	ds_read_b128 v[154:157], v148 offset:1024
	ds_read_b128 v[158:161], v148 offset:2048
	ds_read_b128 v[170:173], v148 offset:3072
	ds_read_b128 v[174:177], v149
	ds_read_b128 v[178:181], v149 offset:1024
	ds_read_b128 v[182:185], v149 offset:2048
	ds_read_b128 v[186:189], v149 offset:3072
	ds_read_b128 v[190:193], v147 offset:32768
	ds_read_b128 v[194:197], v147 offset:33792
	ds_read_b128 v[198:201], v147 offset:34816
	ds_read_b128 v[202:205], v147 offset:35840
	ds_read_b128 v[206:209], v147 offset:36864
	ds_read_b128 v[210:213], v147 offset:37888
	ds_read_b128 v[214:217], v147 offset:38912
	ds_read_b128 v[218:221], v147 offset:39936
	s_add_u32 s18, s62, 0x4000
	s_addc_u32 s19, s63, 0
	s_mov_b32 m0, s66
	s_nop 0
	global_load_lds_dwordx4 v142, s[18:19]
	s_nop 0
	s_mov_b32 m0, s67
	s_nop 0
	global_load_lds_dwordx4 v144, s[18:19]
	s_waitcnt vmcnt(8)
	s_waitcnt lgkmcnt(0)
	s_setprio 1
	s_barrier
	v_mfma_f32_16x16x32_bf16 v[124:127], v[150:153], v[190:193], v[124:127]
	v_mfma_f32_16x16x32_bf16 v[120:123], v[158:161], v[190:193], v[120:123]
	v_mfma_f32_16x16x32_bf16 v[104:107], v[158:161], v[198:201], v[104:107]
	v_mfma_f32_16x16x32_bf16 v[108:111], v[150:153], v[198:201], v[108:111]
	v_mfma_f32_16x16x32_bf16 v[92:95], v[150:153], v[206:209], v[92:95]
	v_mfma_f32_16x16x32_bf16 v[88:91], v[158:161], v[206:209], v[88:91]
	v_mfma_f32_16x16x32_bf16 v[72:75], v[158:161], v[214:217], v[72:75]
	v_mfma_f32_16x16x32_bf16 v[76:79], v[150:153], v[214:217], v[76:79]
	v_mfma_f32_16x16x32_bf16 v[76:79], v[154:157], v[218:221], v[76:79]
	v_mfma_f32_16x16x32_bf16 v[72:75], v[170:173], v[218:221], v[72:75]
	v_mfma_f32_16x16x32_bf16 v[88:91], v[170:173], v[210:213], v[88:91]
	v_mfma_f32_16x16x32_bf16 v[92:95], v[154:157], v[210:213], v[92:95]
	v_mfma_f32_16x16x32_bf16 v[108:111], v[154:157], v[202:205], v[108:111]
	v_mfma_f32_16x16x32_bf16 v[104:107], v[170:173], v[202:205], v[104:107]
	v_mfma_f32_16x16x32_bf16 v[120:123], v[170:173], v[194:197], v[120:123]
	v_mfma_f32_16x16x32_bf16 v[124:127], v[154:157], v[194:197], v[124:127]
	s_setprio 0
	s_setprio 1
	v_mfma_f32_16x16x32_bf16 v[116:119], v[174:177], v[190:193], v[116:119]
	v_mfma_f32_16x16x32_bf16 v[112:115], v[182:185], v[190:193], v[112:115]
	v_mfma_f32_16x16x32_bf16 v[96:99], v[182:185], v[198:201], v[96:99]
	v_mfma_f32_16x16x32_bf16 v[100:103], v[174:177], v[198:201], v[100:103]
	v_mfma_f32_16x16x32_bf16 v[84:87], v[174:177], v[206:209], v[84:87]
	v_mfma_f32_16x16x32_bf16 v[80:83], v[182:185], v[206:209], v[80:83]
	v_mfma_f32_16x16x32_bf16 v[64:67], v[182:185], v[214:217], v[64:67]
	v_mfma_f32_16x16x32_bf16 v[68:71], v[174:177], v[214:217], v[68:71]
	v_mfma_f32_16x16x32_bf16 v[68:71], v[178:181], v[218:221], v[68:71]
	v_mfma_f32_16x16x32_bf16 v[64:67], v[186:189], v[218:221], v[64:67]
	v_mfma_f32_16x16x32_bf16 v[80:83], v[186:189], v[210:213], v[80:83]
	v_mfma_f32_16x16x32_bf16 v[84:87], v[178:181], v[210:213], v[84:87]
	v_mfma_f32_16x16x32_bf16 v[100:103], v[178:181], v[202:205], v[100:103]
	v_mfma_f32_16x16x32_bf16 v[96:99], v[186:189], v[202:205], v[96:99]
	v_mfma_f32_16x16x32_bf16 v[112:115], v[186:189], v[194:197], v[112:115]
	v_mfma_f32_16x16x32_bf16 v[116:119], v[178:181], v[194:197], v[116:119]
	s_setprio 0
	s_barrier
	ds_read_b128 v[190:193], v147 offset:49152
	ds_read_b128 v[194:197], v147 offset:50176
	ds_read_b128 v[198:201], v147 offset:51200
	ds_read_b128 v[202:205], v147 offset:52224
	ds_read_b128 v[206:209], v147 offset:53248
	ds_read_b128 v[210:213], v147 offset:54272
	ds_read_b128 v[214:217], v147 offset:55296
	ds_read_b128 v[218:221], v147 offset:56320
	s_add_u32 s18, s60, 0x8000
	s_addc_u32 s19, s61, 0
	s_mov_b32 m0, s70
	s_nop 0
	global_load_lds_dwordx4 v143, s[18:19]
	s_nop 0
	s_mov_b32 m0, s71
	s_nop 0
	global_load_lds_dwordx4 v145, s[18:19]
	s_add_u32 s18, s60, 0xc000
	s_addc_u32 s19, s61, 0
	s_mov_b32 m0, s83
	s_nop 0
	global_load_lds_dwordx4 v143, s[18:19]
	s_nop 0
	s_mov_b32 m0, s88
	s_nop 0
	global_load_lds_dwordx4 v145, s[18:19]
	s_nop 0
	s_mov_b32 m0, s72
	s_nop 0
	global_load_lds_dwordx4 v142, s[58:59]
	s_nop 0
	s_mov_b32 m0, s81
	s_nop 0
	global_load_lds_dwordx4 v144, s[58:59]
	s_waitcnt vmcnt(8)
	s_waitcnt lgkmcnt(0)
	s_setprio 1
	s_barrier
	v_mfma_f32_16x16x32_bf16 v[60:63], v[150:153], v[190:193], v[60:63]
	v_mfma_f32_16x16x32_bf16 v[56:59], v[158:161], v[190:193], v[56:59]
	v_mfma_f32_16x16x32_bf16 v[40:43], v[158:161], v[198:201], v[40:43]
	v_mfma_f32_16x16x32_bf16 v[44:47], v[150:153], v[198:201], v[44:47]
	v_mfma_f32_16x16x32_bf16 v[28:31], v[150:153], v[206:209], v[28:31]
	v_mfma_f32_16x16x32_bf16 v[24:27], v[158:161], v[206:209], v[24:27]
	v_mfma_f32_16x16x32_bf16 v[8:11], v[158:161], v[214:217], v[8:11]
	v_mfma_f32_16x16x32_bf16 v[12:15], v[150:153], v[214:217], v[12:15]
	v_mfma_f32_16x16x32_bf16 v[12:15], v[154:157], v[218:221], v[12:15]
	v_mfma_f32_16x16x32_bf16 v[8:11], v[170:173], v[218:221], v[8:11]
	v_mfma_f32_16x16x32_bf16 v[24:27], v[170:173], v[210:213], v[24:27]
	v_mfma_f32_16x16x32_bf16 v[28:31], v[154:157], v[210:213], v[28:31]
	v_mfma_f32_16x16x32_bf16 v[44:47], v[154:157], v[202:205], v[44:47]
	v_mfma_f32_16x16x32_bf16 v[40:43], v[170:173], v[202:205], v[40:43]
	v_mfma_f32_16x16x32_bf16 v[56:59], v[170:173], v[194:197], v[56:59]
	v_mfma_f32_16x16x32_bf16 v[60:63], v[154:157], v[194:197], v[60:63]
	s_setprio 0
	s_setprio 1
	v_mfma_f32_16x16x32_bf16 v[52:55], v[174:177], v[190:193], v[52:55]
	v_mfma_f32_16x16x32_bf16 v[48:51], v[182:185], v[190:193], v[48:51]
	v_mfma_f32_16x16x32_bf16 v[32:35], v[182:185], v[198:201], v[32:35]
	v_mfma_f32_16x16x32_bf16 v[36:39], v[174:177], v[198:201], v[36:39]
	v_mfma_f32_16x16x32_bf16 v[20:23], v[174:177], v[206:209], v[20:23]
	v_mfma_f32_16x16x32_bf16 v[16:19], v[182:185], v[206:209], v[16:19]
	v_mfma_f32_16x16x32_bf16 v[0:3], v[182:185], v[214:217], v[0:3]
	v_mfma_f32_16x16x32_bf16 v[4:7], v[174:177], v[214:217], v[4:7]
	v_mfma_f32_16x16x32_bf16 v[4:7], v[178:181], v[218:221], v[4:7]
	v_mfma_f32_16x16x32_bf16 v[0:3], v[186:189], v[218:221], v[0:3]
	v_mfma_f32_16x16x32_bf16 v[16:19], v[186:189], v[210:213], v[16:19]
	v_mfma_f32_16x16x32_bf16 v[20:23], v[178:181], v[210:213], v[20:23]
	v_mfma_f32_16x16x32_bf16 v[36:39], v[178:181], v[202:205], v[36:39]
	v_mfma_f32_16x16x32_bf16 v[32:35], v[186:189], v[202:205], v[32:35]
	v_mfma_f32_16x16x32_bf16 v[48:51], v[186:189], v[194:197], v[48:51]
	v_mfma_f32_16x16x32_bf16 v[52:55], v[178:181], v[194:197], v[52:55]
	s_setprio 0
	s_barrier
	s_add_i32 s16, s16, 2
	s_add_u32 vcc_lo, vcc_lo, 0x10000
	s_addc_u32 vcc_hi, vcc_hi, 0
	s_add_u32 s14, s14, 0x10000
	s_addc_u32 s15, s15, 0
	s_cmp_gt_u32 s16, 61
	s_cbranch_scc0 .LBB0_535
	s_and_b64 vcc, exec, s[48:49]
	s_cbranch_vccz .LBB0_538
	s_barrier

.LBB0_618:
	v_add_u32_e32 v164, 0x10000, v179
	ds_read_b128 v[182:185], v164
	ds_read_b128 v[186:189], v164 offset:1024
	ds_read_b128 v[190:193], v164 offset:2048
	ds_read_b128 v[194:197], v164 offset:3072
	v_add_u32_e32 v164, 0x14000, v179
	ds_read_b128 v[198:201], v164
	ds_read_b128 v[202:205], v164 offset:1024
	ds_read_b128 v[206:209], v164 offset:2048
	ds_read_b128 v[210:213], v164 offset:3072
	s_cmpk_eq_i32 s18, 0xfc
	s_cselect_b32 s66, s16, s55
	s_cselect_b32 s67, s15, s61
	s_cselect_b32 s64, s17, vcc_lo
	s_cselect_b32 s65, s11, vcc_hi
	s_add_u32 s62, s66, 0x8000
	s_addc_u32 s63, s67, 0
	ds_read_b128 v[214:217], v180
	ds_read_b128 v[218:221], v180 offset:1024
	ds_read_b128 v[222:225], v180 offset:2048
	ds_read_b128 v[226:229], v180 offset:3072
	ds_read_b128 v[230:233], v180 offset:4096
	ds_read_b128 v[234:237], v180 offset:5120
	ds_read_b128 v[238:241], v180 offset:6144
	ds_read_b128 v[242:245], v180 offset:7168
	s_add_u32 s28, s55, 0xffffc000
	s_addc_u32 s29, s61, -1
	s_mov_b32 m0, s47
	s_nop 0
	global_load_lds_dwordx4 v176, s[28:29]
	s_nop 0
	s_mov_b32 m0, s94
	s_nop 0
	global_load_lds_dwordx4 v177, s[28:29]
	s_waitcnt vmcnt(8)
	s_waitcnt lgkmcnt(0)
	s_setprio 1
	s_barrier
	v_mfma_f32_16x16x32_bf16 v[0:3], v[182:185], v[214:217], v[0:3]
	v_mfma_f32_16x16x32_bf16 v[4:7], v[190:193], v[214:217], v[4:7]
	v_mfma_f32_16x16x32_bf16 v[24:27], v[190:193], v[222:225], v[24:27]
	v_mfma_f32_16x16x32_bf16 v[12:15], v[182:185], v[222:225], v[12:15]
	v_mfma_f32_16x16x32_bf16 v[44:47], v[182:185], v[230:233], v[44:47]
	v_mfma_f32_16x16x32_bf16 v[56:59], v[190:193], v[230:233], v[56:59]
	v_mfma_f32_16x16x32_bf16 v[80:83], v[190:193], v[238:241], v[80:83]
	v_mfma_f32_16x16x32_bf16 v[68:71], v[182:185], v[238:241], v[68:71]
	v_mfma_f32_16x16x32_bf16 v[68:71], v[186:189], v[242:245], v[68:71]
	v_mfma_f32_16x16x32_bf16 v[80:83], v[194:197], v[242:245], v[80:83]
	v_mfma_f32_16x16x32_bf16 v[56:59], v[194:197], v[234:237], v[56:59]
	v_mfma_f32_16x16x32_bf16 v[44:47], v[186:189], v[234:237], v[44:47]
	v_mfma_f32_16x16x32_bf16 v[12:15], v[186:189], v[226:229], v[12:15]
	v_mfma_f32_16x16x32_bf16 v[24:27], v[194:197], v[226:229], v[24:27]
	v_mfma_f32_16x16x32_bf16 v[4:7], v[194:197], v[218:221], v[4:7]
	v_mfma_f32_16x16x32_bf16 v[0:3], v[186:189], v[218:221], v[0:3]
	s_setprio 0
	s_setprio 1
	v_mfma_f32_16x16x32_bf16 v[20:23], v[198:201], v[214:217], v[20:23]
	v_mfma_f32_16x16x32_bf16 v[36:39], v[206:209], v[214:217], v[36:39]
	v_mfma_f32_16x16x32_bf16 v[60:63], v[206:209], v[222:225], v[60:63]
	v_mfma_f32_16x16x32_bf16 v[48:51], v[198:201], v[222:225], v[48:51]
	v_mfma_f32_16x16x32_bf16 v[72:75], v[198:201], v[230:233], v[72:75]
	v_mfma_f32_16x16x32_bf16 v[88:91], v[206:209], v[230:233], v[88:91]
	v_mfma_f32_16x16x32_bf16 v[104:107], v[206:209], v[238:241], v[104:107]
	v_mfma_f32_16x16x32_bf16 v[96:99], v[198:201], v[238:241], v[96:99]
	v_mfma_f32_16x16x32_bf16 v[96:99], v[202:205], v[242:245], v[96:99]
	v_mfma_f32_16x16x32_bf16 v[104:107], v[210:213], v[242:245], v[104:107]
	v_mfma_f32_16x16x32_bf16 v[88:91], v[210:213], v[234:237], v[88:91]
	v_mfma_f32_16x16x32_bf16 v[72:75], v[202:205], v[234:237], v[72:75]
	v_mfma_f32_16x16x32_bf16 v[48:51], v[202:205], v[226:229], v[48:51]
	v_mfma_f32_16x16x32_bf16 v[60:63], v[210:213], v[226:229], v[60:63]
	v_mfma_f32_16x16x32_bf16 v[36:39], v[210:213], v[218:221], v[36:39]
	v_mfma_f32_16x16x32_bf16 v[20:23], v[202:205], v[218:221], v[20:23]
	s_setprio 0
	s_barrier
	ds_read_b128 v[214:217], v180 offset:16384
	ds_read_b128 v[218:221], v180 offset:17408
	ds_read_b128 v[222:225], v180 offset:18432
	ds_read_b128 v[226:229], v180 offset:19456
	ds_read_b128 v[230:233], v180 offset:20480
	ds_read_b128 v[234:237], v180 offset:21504
	ds_read_b128 v[238:241], v180 offset:22528
	ds_read_b128 v[242:245], v180 offset:23552
	s_mov_b32 m0, s8
	s_nop 0
	global_load_lds_dwordx4 v176, s[64:65]
	s_add_u32 s28, s64, 0x4000
	s_mov_b32 m0, s20
	s_nop 0
	global_load_lds_dwordx4 v177, s[64:65]
	s_addc_u32 s29, s65, 0
	s_mov_b32 m0, s22
	s_nop 0
	global_load_lds_dwordx4 v176, s[28:29]
	s_nop 0
	s_mov_b32 m0, s24
	s_nop 0
	global_load_lds_dwordx4 v177, s[28:29]
	s_nop 0
	s_mov_b32 m0, s83
	s_nop 0
	global_load_lds_dwordx4 v176, s[66:67]
	s_nop 0
	s_mov_b32 m0, s25
	s_nop 0
	global_load_lds_dwordx4 v177, s[66:67]
	s_waitcnt vmcnt(8)
	s_waitcnt lgkmcnt(0)
	s_setprio 1
	s_barrier
	v_mfma_f32_16x16x32_bf16 v[28:31], v[182:185], v[214:217], v[28:31]
	v_mfma_f32_16x16x32_bf16 v[8:11], v[190:193], v[214:217], v[8:11]
	v_mfma_f32_16x16x32_bf16 v[52:55], v[190:193], v[222:225], v[52:55]
	v_mfma_f32_16x16x32_bf16 v[40:43], v[182:185], v[222:225], v[40:43]
	v_mfma_f32_16x16x32_bf16 v[84:87], v[182:185], v[230:233], v[84:87]
	v_mfma_f32_16x16x32_bf16 v[92:95], v[190:193], v[230:233], v[92:95]
	v_mfma_f32_16x16x32_bf16 v[116:119], v[190:193], v[238:241], v[116:119]
	v_mfma_f32_16x16x32_bf16 v[112:115], v[182:185], v[238:241], v[112:115]
	v_mfma_f32_16x16x32_bf16 v[112:115], v[186:189], v[242:245], v[112:115]
	v_mfma_f32_16x16x32_bf16 v[116:119], v[194:197], v[242:245], v[116:119]
	v_mfma_f32_16x16x32_bf16 v[92:95], v[194:197], v[234:237], v[92:95]
	v_mfma_f32_16x16x32_bf16 v[84:87], v[186:189], v[234:237], v[84:87]
	v_mfma_f32_16x16x32_bf16 v[40:43], v[186:189], v[226:229], v[40:43]
	v_mfma_f32_16x16x32_bf16 v[52:55], v[194:197], v[226:229], v[52:55]
	v_mfma_f32_16x16x32_bf16 v[8:11], v[194:197], v[218:221], v[8:11]
	v_mfma_f32_16x16x32_bf16 v[28:31], v[186:189], v[218:221], v[28:31]
	s_setprio 0
	s_setprio 1
	v_mfma_f32_16x16x32_bf16 v[16:19], v[198:201], v[214:217], v[16:19]
	v_mfma_f32_16x16x32_bf16 v[32:35], v[206:209], v[214:217], v[32:35]
	v_mfma_f32_16x16x32_bf16 v[76:79], v[206:209], v[222:225], v[76:79]
	v_mfma_f32_16x16x32_bf16 v[64:67], v[198:201], v[222:225], v[64:67]
	v_mfma_f32_16x16x32_bf16 v[100:103], v[198:201], v[230:233], v[100:103]
	v_mfma_f32_16x16x32_bf16 v[108:111], v[206:209], v[230:233], v[108:111]
	v_mfma_f32_16x16x32_bf16 v[124:127], v[206:209], v[238:241], v[124:127]
	v_mfma_f32_16x16x32_bf16 v[120:123], v[198:201], v[238:241], v[120:123]
	v_mfma_f32_16x16x32_bf16 v[120:123], v[202:205], v[242:245], v[120:123]
	v_mfma_f32_16x16x32_bf16 v[124:127], v[210:213], v[242:245], v[124:127]
	v_mfma_f32_16x16x32_bf16 v[108:111], v[210:213], v[234:237], v[108:111]
	v_mfma_f32_16x16x32_bf16 v[100:103], v[202:205], v[234:237], v[100:103]
	v_mfma_f32_16x16x32_bf16 v[64:67], v[202:205], v[226:229], v[64:67]
	v_mfma_f32_16x16x32_bf16 v[76:79], v[210:213], v[226:229], v[76:79]
	v_mfma_f32_16x16x32_bf16 v[32:35], v[210:213], v[218:221], v[32:35]
	v_mfma_f32_16x16x32_bf16 v[16:19], v[202:205], v[218:221], v[16:19]
	s_setprio 0
	s_barrier
	v_add_u32_e32 v164, 0x18000, v179
	ds_read_b128 v[182:185], v164
	ds_read_b128 v[186:189], v164 offset:1024
	ds_read_b128 v[190:193], v164 offset:2048
	ds_read_b128 v[194:197], v164 offset:3072
	v_add_u32_e32 v164, 0x1c000, v179
	ds_read_b128 v[198:201], v164
	ds_read_b128 v[202:205], v164 offset:1024
	ds_read_b128 v[206:209], v164 offset:2048
	ds_read_b128 v[210:213], v164 offset:3072
	ds_read_b128 v[214:217], v180 offset:32768
	ds_read_b128 v[218:221], v180 offset:33792
	ds_read_b128 v[222:225], v180 offset:34816
	ds_read_b128 v[226:229], v180 offset:35840
	ds_read_b128 v[230:233], v180 offset:36864
	ds_read_b128 v[234:237], v180 offset:37888
	ds_read_b128 v[238:241], v180 offset:38912
	ds_read_b128 v[242:245], v180 offset:39936
	s_add_u32 s28, s66, 0x4000
	s_addc_u32 s29, s67, 0
	s_mov_b32 m0, s4
	s_nop 0
	global_load_lds_dwordx4 v176, s[28:29]
	s_nop 0
	s_mov_b32 m0, s5
	s_nop 0
	global_load_lds_dwordx4 v177, s[28:29]
	s_waitcnt vmcnt(8)
	s_waitcnt lgkmcnt(0)
	s_setprio 1
	s_barrier
	v_mfma_f32_16x16x32_bf16 v[0:3], v[182:185], v[214:217], v[0:3]
	v_mfma_f32_16x16x32_bf16 v[4:7], v[190:193], v[214:217], v[4:7]
	v_mfma_f32_16x16x32_bf16 v[24:27], v[190:193], v[222:225], v[24:27]
	v_mfma_f32_16x16x32_bf16 v[12:15], v[182:185], v[222:225], v[12:15]
	v_mfma_f32_16x16x32_bf16 v[44:47], v[182:185], v[230:233], v[44:47]
	v_mfma_f32_16x16x32_bf16 v[56:59], v[190:193], v[230:233], v[56:59]
	v_mfma_f32_16x16x32_bf16 v[80:83], v[190:193], v[238:241], v[80:83]
	v_mfma_f32_16x16x32_bf16 v[68:71], v[182:185], v[238:241], v[68:71]
	v_mfma_f32_16x16x32_bf16 v[68:71], v[186:189], v[242:245], v[68:71]
	v_mfma_f32_16x16x32_bf16 v[80:83], v[194:197], v[242:245], v[80:83]
	v_mfma_f32_16x16x32_bf16 v[56:59], v[194:197], v[234:237], v[56:59]
	v_mfma_f32_16x16x32_bf16 v[44:47], v[186:189], v[234:237], v[44:47]
	v_mfma_f32_16x16x32_bf16 v[12:15], v[186:189], v[226:229], v[12:15]
	v_mfma_f32_16x16x32_bf16 v[24:27], v[194:197], v[226:229], v[24:27]
	v_mfma_f32_16x16x32_bf16 v[4:7], v[194:197], v[218:221], v[4:7]
	v_mfma_f32_16x16x32_bf16 v[0:3], v[186:189], v[218:221], v[0:3]
	s_setprio 0
	s_setprio 1
	v_mfma_f32_16x16x32_bf16 v[20:23], v[198:201], v[214:217], v[20:23]
	v_mfma_f32_16x16x32_bf16 v[36:39], v[206:209], v[214:217], v[36:39]
	v_mfma_f32_16x16x32_bf16 v[60:63], v[206:209], v[222:225], v[60:63]
	v_mfma_f32_16x16x32_bf16 v[48:51], v[198:201], v[222:225], v[48:51]
	v_mfma_f32_16x16x32_bf16 v[72:75], v[198:201], v[230:233], v[72:75]
	v_mfma_f32_16x16x32_bf16 v[88:91], v[206:209], v[230:233], v[88:91]
	v_mfma_f32_16x16x32_bf16 v[104:107], v[206:209], v[238:241], v[104:107]
	v_mfma_f32_16x16x32_bf16 v[96:99], v[198:201], v[238:241], v[96:99]
	v_mfma_f32_16x16x32_bf16 v[96:99], v[202:205], v[242:245], v[96:99]
	v_mfma_f32_16x16x32_bf16 v[104:107], v[210:213], v[242:245], v[104:107]
	v_mfma_f32_16x16x32_bf16 v[88:91], v[210:213], v[234:237], v[88:91]
	v_mfma_f32_16x16x32_bf16 v[72:75], v[202:205], v[234:237], v[72:75]
	v_mfma_f32_16x16x32_bf16 v[48:51], v[202:205], v[226:229], v[48:51]
	v_mfma_f32_16x16x32_bf16 v[60:63], v[210:213], v[226:229], v[60:63]
	v_mfma_f32_16x16x32_bf16 v[36:39], v[210:213], v[218:221], v[36:39]
	v_mfma_f32_16x16x32_bf16 v[20:23], v[202:205], v[218:221], v[20:23]
	s_setprio 0
	s_barrier
	ds_read_b128 v[214:217], v180 offset:49152
	ds_read_b128 v[218:221], v180 offset:50176
	ds_read_b128 v[222:225], v180 offset:51200
	ds_read_b128 v[226:229], v180 offset:52224
	ds_read_b128 v[230:233], v180 offset:53248
	ds_read_b128 v[234:237], v180 offset:54272
	ds_read_b128 v[238:241], v180 offset:55296
	ds_read_b128 v[242:245], v180 offset:56320
	s_add_u32 s28, s64, 0x8000
	s_addc_u32 s29, s65, 0
	s_mov_b32 m0, s70
	s_nop 0
	global_load_lds_dwordx4 v176, s[28:29]
	s_nop 0
	s_mov_b32 m0, s71
	s_nop 0
	global_load_lds_dwordx4 v177, s[28:29]
	s_add_u32 s28, s64, 0xc000
	s_addc_u32 s29, s65, 0
	s_mov_b32 m0, s45
	s_nop 0
	global_load_lds_dwordx4 v176, s[28:29]
	s_nop 0
	s_mov_b32 m0, s46
	s_nop 0
	global_load_lds_dwordx4 v177, s[28:29]
	s_nop 0
	s_mov_b32 m0, s72
	s_nop 0
	global_load_lds_dwordx4 v176, s[62:63]
	s_nop 0
	s_mov_b32 m0, s44
	s_nop 0
	global_load_lds_dwordx4 v177, s[62:63]
	s_waitcnt vmcnt(8)
	s_waitcnt lgkmcnt(0)
	s_setprio 1
	s_barrier
	v_mfma_f32_16x16x32_bf16 v[28:31], v[182:185], v[214:217], v[28:31]
	v_mfma_f32_16x16x32_bf16 v[8:11], v[190:193], v[214:217], v[8:11]
	v_mfma_f32_16x16x32_bf16 v[52:55], v[190:193], v[222:225], v[52:55]
	v_mfma_f32_16x16x32_bf16 v[40:43], v[182:185], v[222:225], v[40:43]
	v_mfma_f32_16x16x32_bf16 v[84:87], v[182:185], v[230:233], v[84:87]
	v_mfma_f32_16x16x32_bf16 v[92:95], v[190:193], v[230:233], v[92:95]
	v_mfma_f32_16x16x32_bf16 v[116:119], v[190:193], v[238:241], v[116:119]
	v_mfma_f32_16x16x32_bf16 v[112:115], v[182:185], v[238:241], v[112:115]
	v_mfma_f32_16x16x32_bf16 v[112:115], v[186:189], v[242:245], v[112:115]
	v_mfma_f32_16x16x32_bf16 v[116:119], v[194:197], v[242:245], v[116:119]
	v_mfma_f32_16x16x32_bf16 v[92:95], v[194:197], v[234:237], v[92:95]
	v_mfma_f32_16x16x32_bf16 v[84:87], v[186:189], v[234:237], v[84:87]
	v_mfma_f32_16x16x32_bf16 v[40:43], v[186:189], v[226:229], v[40:43]
	v_mfma_f32_16x16x32_bf16 v[52:55], v[194:197], v[226:229], v[52:55]
	v_mfma_f32_16x16x32_bf16 v[8:11], v[194:197], v[218:221], v[8:11]
	v_mfma_f32_16x16x32_bf16 v[28:31], v[186:189], v[218:221], v[28:31]
	s_setprio 0
	s_setprio 1
	v_mfma_f32_16x16x32_bf16 v[16:19], v[198:201], v[214:217], v[16:19]
	v_mfma_f32_16x16x32_bf16 v[32:35], v[206:209], v[214:217], v[32:35]
	v_mfma_f32_16x16x32_bf16 v[76:79], v[206:209], v[222:225], v[76:79]
	v_mfma_f32_16x16x32_bf16 v[64:67], v[198:201], v[222:225], v[64:67]
	v_mfma_f32_16x16x32_bf16 v[100:103], v[198:201], v[230:233], v[100:103]
	v_mfma_f32_16x16x32_bf16 v[108:111], v[206:209], v[230:233], v[108:111]
	v_mfma_f32_16x16x32_bf16 v[124:127], v[206:209], v[238:241], v[124:127]
	v_mfma_f32_16x16x32_bf16 v[120:123], v[198:201], v[238:241], v[120:123]
	v_mfma_f32_16x16x32_bf16 v[120:123], v[202:205], v[242:245], v[120:123]
	v_mfma_f32_16x16x32_bf16 v[124:127], v[210:213], v[242:245], v[124:127]
	v_mfma_f32_16x16x32_bf16 v[108:111], v[210:213], v[234:237], v[108:111]
	v_mfma_f32_16x16x32_bf16 v[100:103], v[202:205], v[234:237], v[100:103]
	v_mfma_f32_16x16x32_bf16 v[64:67], v[202:205], v[226:229], v[64:67]
	v_mfma_f32_16x16x32_bf16 v[76:79], v[210:213], v[226:229], v[76:79]
	v_mfma_f32_16x16x32_bf16 v[32:35], v[210:213], v[218:221], v[32:35]
	v_mfma_f32_16x16x32_bf16 v[16:19], v[202:205], v[218:221], v[16:19]
	s_setprio 0
	s_barrier
	s_add_i32 s18, s18, 2
	s_add_u32 s55, s55, 0x10000
	s_addc_u32 s61, s61, 0
	s_add_u32 vcc_lo, vcc_lo, 0x10000
	s_addc_u32 vcc_hi, vcc_hi, 0
	s_cmpk_gt_u32 s18, 0xfd
	s_cbranch_scc0 .LBB0_618
	s_and_b64 vcc, exec, s[48:49]
	s_cbranch_vccz .LBB0_621
	s_barrier
	s_andn2_b64 vcc, exec, s[36:37]
	s_cbranch_vccnz .LBB0_623
	s_branch .LBB0_622
